# v109 + one static s_setprio 1 for waves 4-7 during the GQA attention phase (reset at phase exit)
# speedup vs baseline: 1.0055x; 1.0015x over previous
.LBB0_1191:
	v_readlane_b32 s2, v255, 11
	s_add_i32 s2, s2, 8
	v_readlane_b32 s8, v253, 4
	v_readlane_b32 s9, v253, 5
	s_cmp_le_i32 s8, s2
	s_cselect_b64 s[4:5], -1, 0
	s_cmp_lt_i32 s2, s9
	s_cselect_b64 s[8:9], -1, 0
	s_and_b64 s[38:39], s[4:5], s[8:9]
	s_andn2_b64 vcc, exec, s[38:39]
	v_readlane_b32 s10, v253, 6
	v_readlane_b32 s11, v253, 7
	s_cbranch_vccnz .LBB0_1242
	s_barrier
	s_cmpk_gt_i32 s92, 0x1ff
	s_waitcnt vmcnt(0)
	v_mbcnt_lo_u32_b32 v0, -1, 0
	v_mbcnt_hi_u32_b32 v0, -1, v0
	s_cbranch_scc1 .LBB0_1242
	s_cmp_ge_u32 s93, 4
	s_cbranch_scc0 .Lgqa_prio_done
	s_setprio 1
.Lgqa_prio_done:
	s_add_u32 s10, s74, 0x2d200000
	s_addc_u32 s24, s75, 0
	s_add_u32 s48, s74, 0x2e300000
	s_addc_u32 s49, s75, 0
	s_add_u32 s50, s74, 0x2e800000
	s_addc_u32 s51, s75, 0
	s_add_u32 s52, s74, 0x2fe00000
	s_addc_u32 s53, s75, 0
	s_add_u32 s54, s74, 0x2e304000
	s_addc_u32 s55, s75, 0
	s_add_u32 s40, s74, 0x2e804000
	s_addc_u32 s41, s75, 0
	s_mov_b32 s56, s92
	s_branch .LBB0_1195

.LBB0_1242:
	s_setprio 0
	v_readlane_b32 s2, v255, 11
	v_readlane_b32 s8, v253, 4
	s_add_i32 s2, s2, 9
	v_readlane_b32 s9, v253, 5
	s_cmp_gt_i32 s9, s2
	s_cselect_b64 s[36:37], -1, 0
	s_and_b64 s[4:5], s[38:39], s[36:37]
	s_andn2_b64 vcc, exec, s[4:5]
	v_readlane_b32 s10, v253, 6
	v_readlane_b32 s11, v253, 7
	s_cbranch_vccnz .LBB0_1292
	s_waitcnt vmcnt(0)
	v_readlane_b32 s4, v253, 8
	s_barrier
	s_waitcnt vmcnt(0)
	v_mbcnt_lo_u32_b32 v0, -1, 0
	v_mbcnt_hi_u32_b32 v0, -1, v0
	v_readlane_b32 s5, v253, 9
	v_cmp_eq_u32_e32 vcc, 0, v0
	s_and_b64 s[4:5], s[4:5], vcc
	s_and_saveexec_b64 s[38:39], s[4:5]
	s_cbranch_execz .LBB0_1291
	v_readlane_b32 s4, v254, 53
	s_waitcnt vmcnt(0) expcnt(0) lgkmcnt(0)
	s_nop 0
	v_mov_b32_e32 v0, s4
	ds_read_b32 v2, v0
	v_readlane_b32 s4, v254, 54
	s_waitcnt lgkmcnt(0)
	v_cmp_ne_u32_e32 vcc, 0, v2
	v_mov_b32_e32 v0, s4
	ds_read_b32 v0, v0
	s_cbranch_vccnz .LBB0_1259
	v_readlane_b32 s8, v253, 2
	v_readlane_b32 s9, v253, 3
	s_load_dwordx2 s[4:5], s[8:9], 0x4
	s_waitcnt lgkmcnt(0)
	s_mul_i32 s4, s4, s94
	s_mul_i32 s4, s4, s5
	s_mov_b32 s5, 1
	s_branch .LBB0_1247
